# stack15: stack13 + P4 cmp pass-B importance quad-sums rewritten (two v_add_f32_dpp steps, one exec window per 4 values, exp issued in hazard slots)
# speedup vs baseline: 1.0002x; 1.0002x over previous
.LBB0_1327:
	v_add_u32_e32 v106, s2, v201
	ds_read_b64_tr_b16 v[134:135], v106 offset:18432
	ds_read_b64_tr_b16 v[136:137], v106 offset:19584
	ds_read_b64_tr_b16 v[120:121], v106 offset:19648
	ds_read_b64_tr_b16 v[118:119], v106 offset:18496
	ds_read_b64_tr_b16 v[130:131], v106 offset:20736
	ds_read_b64_tr_b16 v[132:133], v106 offset:21888
	ds_read_b64_tr_b16 v[116:117], v106 offset:21952
	ds_read_b64_tr_b16 v[114:115], v106 offset:20800
	ds_read_b64_tr_b16 v[126:127], v106 offset:23040
	ds_read_b64_tr_b16 v[128:129], v106 offset:24192
	ds_read_b64_tr_b16 v[112:113], v106 offset:24256
	ds_read_b64_tr_b16 v[110:111], v106 offset:23104
	ds_read_b64_tr_b16 v[122:123], v106 offset:25344
	ds_read_b64_tr_b16 v[124:125], v106 offset:26496
	ds_read_b64_tr_b16 v[108:109], v106 offset:26560
	ds_read_b64_tr_b16 v[106:107], v106 offset:25408
	v_add_u32_e32 v146, 0x9000, v199
	v_exp_f32_e32 v66, v66
	v_exp_f32_e32 v50, v50
	v_exp_f32_e32 v67, v67
	v_exp_f32_e32 v51, v51
	v_pk_mul_f32 v[66:67], v[164:165], v[66:67]
	v_pk_mul_f32 v[50:51], v[164:165], v[50:51]
	v_exp_f32_e32 v68, v68
	v_exp_f32_e32 v52, v52
	v_exp_f32_e32 v69, v69
	v_exp_f32_e32 v53, v53
	v_add_f32_dpp v237, v66, v66 quad_perm:[1,0,3,2] row_mask:0xf bank_mask:0xf bound_ctrl:1
	v_add_f32_dpp v238, v50, v50 quad_perm:[1,0,3,2] row_mask:0xf bank_mask:0xf bound_ctrl:1
	v_add_f32_dpp v239, v67, v67 quad_perm:[1,0,3,2] row_mask:0xf bank_mask:0xf bound_ctrl:1
	v_add_f32_dpp v240, v51, v51 quad_perm:[1,0,3,2] row_mask:0xf bank_mask:0xf bound_ctrl:1
	v_add_f32_dpp v237, v237, v237 quad_perm:[2,3,0,1] row_mask:0xf bank_mask:0xf bound_ctrl:1
	v_add_f32_dpp v238, v238, v238 quad_perm:[2,3,0,1] row_mask:0xf bank_mask:0xf bound_ctrl:1
	v_add_f32_dpp v239, v239, v239 quad_perm:[2,3,0,1] row_mask:0xf bank_mask:0xf bound_ctrl:1
	v_add_f32_dpp v240, v240, v240 quad_perm:[2,3,0,1] row_mask:0xf bank_mask:0xf bound_ctrl:1
	v_pk_mul_f32 v[68:69], v[164:165], v[68:69]
	v_pk_mul_f32 v[52:53], v[164:165], v[52:53]
	s_and_saveexec_b64 s[2:3], s[26:27]
	ds_write2_b32 v146, v237, v238 offset0:1 offset1:33
	ds_write2_b32 v146, v239, v240 offset0:2 offset1:34
	s_or_b64 exec, exec, s[2:3]
	v_exp_f32_e32 v70, v70
	v_exp_f32_e32 v54, v54
	v_exp_f32_e32 v71, v71
	v_exp_f32_e32 v55, v55
	v_add_f32_dpp v237, v68, v68 quad_perm:[1,0,3,2] row_mask:0xf bank_mask:0xf bound_ctrl:1
	v_add_f32_dpp v238, v52, v52 quad_perm:[1,0,3,2] row_mask:0xf bank_mask:0xf bound_ctrl:1
	v_add_f32_dpp v239, v69, v69 quad_perm:[1,0,3,2] row_mask:0xf bank_mask:0xf bound_ctrl:1
	v_add_f32_dpp v240, v53, v53 quad_perm:[1,0,3,2] row_mask:0xf bank_mask:0xf bound_ctrl:1
	v_add_f32_dpp v237, v237, v237 quad_perm:[2,3,0,1] row_mask:0xf bank_mask:0xf bound_ctrl:1
	v_add_f32_dpp v238, v238, v238 quad_perm:[2,3,0,1] row_mask:0xf bank_mask:0xf bound_ctrl:1
	v_add_f32_dpp v239, v239, v239 quad_perm:[2,3,0,1] row_mask:0xf bank_mask:0xf bound_ctrl:1
	v_add_f32_dpp v240, v240, v240 quad_perm:[2,3,0,1] row_mask:0xf bank_mask:0xf bound_ctrl:1
	v_pk_mul_f32 v[70:71], v[164:165], v[70:71]
	v_pk_mul_f32 v[54:55], v[164:165], v[54:55]
	s_and_saveexec_b64 s[2:3], s[26:27]
	ds_write2_b32 v208, v237, v238 offset0:1 offset1:33
	ds_write2_b32 v209, v239, v240 offset0:1 offset1:33
	s_or_b64 exec, exec, s[2:3]
	v_exp_f32_e32 v72, v72
	v_exp_f32_e32 v56, v56
	v_exp_f32_e32 v73, v73
	v_exp_f32_e32 v57, v57
	v_add_f32_dpp v237, v70, v70 quad_perm:[1,0,3,2] row_mask:0xf bank_mask:0xf bound_ctrl:1
	v_add_f32_dpp v238, v54, v54 quad_perm:[1,0,3,2] row_mask:0xf bank_mask:0xf bound_ctrl:1
	v_add_f32_dpp v239, v71, v71 quad_perm:[1,0,3,2] row_mask:0xf bank_mask:0xf bound_ctrl:1
	v_add_f32_dpp v240, v55, v55 quad_perm:[1,0,3,2] row_mask:0xf bank_mask:0xf bound_ctrl:1
	v_add_f32_dpp v237, v237, v237 quad_perm:[2,3,0,1] row_mask:0xf bank_mask:0xf bound_ctrl:1
	v_add_f32_dpp v238, v238, v238 quad_perm:[2,3,0,1] row_mask:0xf bank_mask:0xf bound_ctrl:1
	v_add_f32_dpp v239, v239, v239 quad_perm:[2,3,0,1] row_mask:0xf bank_mask:0xf bound_ctrl:1
	v_add_f32_dpp v240, v240, v240 quad_perm:[2,3,0,1] row_mask:0xf bank_mask:0xf bound_ctrl:1
	v_pk_mul_f32 v[166:167], v[164:165], v[72:73]
	v_pk_mul_f32 v[56:57], v[164:165], v[56:57]
	s_and_saveexec_b64 s[2:3], s[26:27]
	ds_write2_b32 v210, v237, v238 offset0:1 offset1:33
	ds_write2_b32 v211, v239, v240 offset0:1 offset1:33
	s_or_b64 exec, exec, s[2:3]
	v_exp_f32_e32 v72, v74
	v_exp_f32_e32 v58, v58
	v_exp_f32_e32 v73, v75
	v_exp_f32_e32 v59, v59
	v_add_f32_dpp v237, v166, v166 quad_perm:[1,0,3,2] row_mask:0xf bank_mask:0xf bound_ctrl:1
	v_add_f32_dpp v238, v56, v56 quad_perm:[1,0,3,2] row_mask:0xf bank_mask:0xf bound_ctrl:1
	v_add_f32_dpp v239, v167, v167 quad_perm:[1,0,3,2] row_mask:0xf bank_mask:0xf bound_ctrl:1
	v_add_f32_dpp v240, v57, v57 quad_perm:[1,0,3,2] row_mask:0xf bank_mask:0xf bound_ctrl:1
	v_add_f32_dpp v237, v237, v237 quad_perm:[2,3,0,1] row_mask:0xf bank_mask:0xf bound_ctrl:1
	v_add_f32_dpp v238, v238, v238 quad_perm:[2,3,0,1] row_mask:0xf bank_mask:0xf bound_ctrl:1
	v_add_f32_dpp v239, v239, v239 quad_perm:[2,3,0,1] row_mask:0xf bank_mask:0xf bound_ctrl:1
	v_add_f32_dpp v240, v240, v240 quad_perm:[2,3,0,1] row_mask:0xf bank_mask:0xf bound_ctrl:1
	v_pk_mul_f32 v[72:73], v[164:165], v[72:73]
	v_pk_mul_f32 v[58:59], v[164:165], v[58:59]
	s_and_saveexec_b64 s[2:3], s[26:27]
	ds_write2_b32 v212, v237, v238 offset0:1 offset1:33
	ds_write2_b32 v213, v239, v240 offset0:1 offset1:33
	s_or_b64 exec, exec, s[2:3]
	v_exp_f32_e32 v74, v76
	v_exp_f32_e32 v60, v60
	v_exp_f32_e32 v75, v77
	v_exp_f32_e32 v61, v61
	v_add_f32_dpp v237, v72, v72 quad_perm:[1,0,3,2] row_mask:0xf bank_mask:0xf bound_ctrl:1
	v_add_f32_dpp v238, v58, v58 quad_perm:[1,0,3,2] row_mask:0xf bank_mask:0xf bound_ctrl:1
	v_add_f32_dpp v239, v73, v73 quad_perm:[1,0,3,2] row_mask:0xf bank_mask:0xf bound_ctrl:1
	v_add_f32_dpp v240, v59, v59 quad_perm:[1,0,3,2] row_mask:0xf bank_mask:0xf bound_ctrl:1
	v_add_f32_dpp v237, v237, v237 quad_perm:[2,3,0,1] row_mask:0xf bank_mask:0xf bound_ctrl:1
	v_add_f32_dpp v238, v238, v238 quad_perm:[2,3,0,1] row_mask:0xf bank_mask:0xf bound_ctrl:1
	v_add_f32_dpp v239, v239, v239 quad_perm:[2,3,0,1] row_mask:0xf bank_mask:0xf bound_ctrl:1
	v_add_f32_dpp v240, v240, v240 quad_perm:[2,3,0,1] row_mask:0xf bank_mask:0xf bound_ctrl:1
	v_pk_mul_f32 v[74:75], v[164:165], v[74:75]
	v_pk_mul_f32 v[60:61], v[164:165], v[60:61]
	s_and_saveexec_b64 s[2:3], s[26:27]
	ds_write2_b32 v215, v237, v238 offset0:1 offset1:33
	ds_write2_b32 v216, v239, v240 offset0:1 offset1:33
	s_or_b64 exec, exec, s[2:3]
	v_exp_f32_e32 v76, v78
	v_exp_f32_e32 v62, v62
	v_exp_f32_e32 v77, v79
	v_exp_f32_e32 v63, v63
	v_add_f32_dpp v237, v74, v74 quad_perm:[1,0,3,2] row_mask:0xf bank_mask:0xf bound_ctrl:1
	v_add_f32_dpp v238, v60, v60 quad_perm:[1,0,3,2] row_mask:0xf bank_mask:0xf bound_ctrl:1
	v_add_f32_dpp v239, v75, v75 quad_perm:[1,0,3,2] row_mask:0xf bank_mask:0xf bound_ctrl:1
	v_add_f32_dpp v240, v61, v61 quad_perm:[1,0,3,2] row_mask:0xf bank_mask:0xf bound_ctrl:1
	v_add_f32_dpp v237, v237, v237 quad_perm:[2,3,0,1] row_mask:0xf bank_mask:0xf bound_ctrl:1
	v_add_f32_dpp v238, v238, v238 quad_perm:[2,3,0,1] row_mask:0xf bank_mask:0xf bound_ctrl:1
	v_add_f32_dpp v239, v239, v239 quad_perm:[2,3,0,1] row_mask:0xf bank_mask:0xf bound_ctrl:1
	v_add_f32_dpp v240, v240, v240 quad_perm:[2,3,0,1] row_mask:0xf bank_mask:0xf bound_ctrl:1
	v_pk_mul_f32 v[76:77], v[164:165], v[76:77]
	v_pk_mul_f32 v[62:63], v[164:165], v[62:63]
	s_and_saveexec_b64 s[2:3], s[26:27]
	ds_write2_b32 v217, v237, v238 offset0:1 offset1:33
	ds_write2_b32 v218, v239, v240 offset0:1 offset1:33
	s_or_b64 exec, exec, s[2:3]
	v_exp_f32_e32 v78, v80
	v_exp_f32_e32 v64, v64
	v_exp_f32_e32 v79, v81
	v_exp_f32_e32 v65, v65
	v_add_f32_dpp v237, v76, v76 quad_perm:[1,0,3,2] row_mask:0xf bank_mask:0xf bound_ctrl:1
	v_add_f32_dpp v238, v62, v62 quad_perm:[1,0,3,2] row_mask:0xf bank_mask:0xf bound_ctrl:1
	v_add_f32_dpp v239, v77, v77 quad_perm:[1,0,3,2] row_mask:0xf bank_mask:0xf bound_ctrl:1
	v_add_f32_dpp v240, v63, v63 quad_perm:[1,0,3,2] row_mask:0xf bank_mask:0xf bound_ctrl:1
	v_add_f32_dpp v237, v237, v237 quad_perm:[2,3,0,1] row_mask:0xf bank_mask:0xf bound_ctrl:1
	v_add_f32_dpp v238, v238, v238 quad_perm:[2,3,0,1] row_mask:0xf bank_mask:0xf bound_ctrl:1
	v_add_f32_dpp v239, v239, v239 quad_perm:[2,3,0,1] row_mask:0xf bank_mask:0xf bound_ctrl:1
	v_add_f32_dpp v240, v240, v240 quad_perm:[2,3,0,1] row_mask:0xf bank_mask:0xf bound_ctrl:1
	v_pk_mul_f32 v[78:79], v[164:165], v[78:79]
	v_pk_mul_f32 v[64:65], v[164:165], v[64:65]
	s_and_saveexec_b64 s[2:3], s[26:27]
	ds_write2_b32 v219, v237, v238 offset0:1 offset1:33
	ds_write2_b32 v220, v239, v240 offset0:1 offset1:33
	s_or_b64 exec, exec, s[2:3]
	v_add_f32_dpp v237, v78, v78 quad_perm:[1,0,3,2] row_mask:0xf bank_mask:0xf bound_ctrl:1
	v_add_f32_dpp v238, v64, v64 quad_perm:[1,0,3,2] row_mask:0xf bank_mask:0xf bound_ctrl:1
	v_add_f32_dpp v239, v79, v79 quad_perm:[1,0,3,2] row_mask:0xf bank_mask:0xf bound_ctrl:1
	v_add_f32_dpp v240, v65, v65 quad_perm:[1,0,3,2] row_mask:0xf bank_mask:0xf bound_ctrl:1
	v_add_f32_dpp v237, v237, v237 quad_perm:[2,3,0,1] row_mask:0xf bank_mask:0xf bound_ctrl:1
	v_add_f32_dpp v238, v238, v238 quad_perm:[2,3,0,1] row_mask:0xf bank_mask:0xf bound_ctrl:1
	v_add_f32_dpp v239, v239, v239 quad_perm:[2,3,0,1] row_mask:0xf bank_mask:0xf bound_ctrl:1
	v_add_f32_dpp v240, v240, v240 quad_perm:[2,3,0,1] row_mask:0xf bank_mask:0xf bound_ctrl:1
	s_and_saveexec_b64 s[2:3], s[26:27]
	ds_write2_b32 v221, v237, v238 offset0:1 offset1:33
	ds_write2_b32 v222, v239, v240 offset0:1 offset1:33
	s_or_b64 exec, exec, s[2:3]
	v_cvt_pk_bf16_f32 v66, v66, v67
	v_cvt_pk_bf16_f32 v67, v68, v69
	v_cvt_pk_bf16_f32 v68, v70, v71
	v_cvt_pk_bf16_f32 v69, v166, v167
	v_cvt_pk_bf16_f32 v70, v72, v73
	v_cvt_pk_bf16_f32 v71, v74, v75
	s_waitcnt lgkmcnt(14)
	v_mfma_f32_32x32x16_bf16 v[34:49], v[134:137], v[66:69], v[34:49]
	v_cvt_pk_bf16_f32 v72, v76, v77
	v_cvt_pk_bf16_f32 v73, v78, v79
	v_cvt_pk_bf16_f32 v50, v50, v51
	v_cvt_pk_bf16_f32 v51, v52, v53
	v_cvt_pk_bf16_f32 v52, v54, v55
	v_cvt_pk_bf16_f32 v54, v58, v59
	v_cvt_pk_bf16_f32 v55, v60, v61
	s_waitcnt lgkmcnt(12)
	v_mfma_f32_32x32x16_bf16 v[18:33], v[118:121], v[66:69], v[18:33]
	s_waitcnt lgkmcnt(0)
	v_add_u32_e32 v58, 0x9000, v205
	v_add_u32_e32 v60, 0x9008, v205
	ds_read2_b32 v[58:59], v58 offset1:1
	ds_read2_b32 v[60:61], v60 offset1:1
	v_cvt_pk_bf16_f32 v53, v56, v57
	v_cvt_pk_bf16_f32 v56, v62, v63
	ds_read_b32 v63, v205 offset:36880
	s_waitcnt lgkmcnt(13)
	v_mfma_f32_32x32x16_bf16 v[34:49], v[130:133], v[70:73], v[34:49]
	s_waitcnt lgkmcnt(1)
	v_add_f32_e32 v59, v59, v60
	v_add_f32_e32 v59, v59, v61
	v_fmac_f32_e32 v58, 2.0, v59
	v_add_u32_e32 v62, s5, v203
	s_waitcnt lgkmcnt(0)
	v_add_f32_e32 v58, v63, v58
	ds_write_b32 v62, v58
	v_add_u32_e32 v58, 0x9014, v205
	v_mfma_f32_32x32x16_bf16 v[18:33], v[114:117], v[70:73], v[18:33]
	v_add_u32_e32 v59, 0x901c, v205
	v_cvt_pk_bf16_f32 v57, v64, v65
	v_mfma_f32_32x32x16_bf16 v[34:49], v[126:129], v[50:53], v[34:49]
	v_mfma_f32_32x32x16_bf16 v[18:33], v[110:113], v[50:53], v[18:33]
	ds_read2_b32 v[50:51], v58 offset1:1
	ds_read2_b32 v[52:53], v59 offset1:1
	s_waitcnt lgkmcnt(1)
	v_add_f32_e32 v50, v50, v51
	s_waitcnt lgkmcnt(0)
	v_add_f32_e32 v50, v50, v52
	v_fmac_f32_e32 v63, 2.0, v50
	v_mfma_f32_32x32x16_bf16 v[34:49], v[122:125], v[54:57], v[34:49]
	v_add_f32_e32 v50, v53, v63
	ds_write_b32 v62, v50 offset:4
	s_waitcnt lgkmcnt(0)
	v_mfma_f32_32x32x16_bf16 v[18:33], v[106:109], v[54:57], v[18:33]
	s_and_saveexec_b64 s[2:3], s[40:41]
	s_cbranch_execz .LBB0_1361
	ds_read_b32 v50, v206 offset:37120
	s_waitcnt lgkmcnt(0)
	ds_write_b32 v206, v50 offset:36864
